# P4 residual x loads with nt cache policy (read once; keeps MIXED / W_out in L2)
# speedup vs baseline: 1.0136x; 1.0136x over previous
.LBB0_927:
	s_or_b64 exec, exec, s[8:9]
	s_mov_b64 s[98:99], s[36:37]
	s_cmp_eq_u32 s39, 0
	s_cbranch_scc1 .Lp4x_skip_w0
	s_lshr_b32 s44, s39, 8
	s_lshl_b32 s52, s44, 6
	s_lshl_b32 s5, s4, 8
	s_add_i32 s5, s5, s52
	v_or_b32_e32 v4, s5, v3
	v_ashrrev_i32_e32 v5, 31, v4
	v_lshlrev_b64 v[4:5], 12, v[4:5]
	s_lshl_b32 s8, s16, 8
	s_bfe_u32 s3, s39, 0x20006
	v_lshl_add_u64 v[4:5], s[36:37], 0, v[4:5]
	s_ashr_i32 s9, s8, 31
	v_lshl_add_u64 v[4:5], s[8:9], 2, v[4:5]
	s_lshl_b32 s8, s3, 8
	s_mov_b32 s9, 0
	v_mov_b32_e32 v159, 0
	v_lshl_add_u64 v[4:5], v[4:5], 0, s[8:9]
	v_lshlrev_b32_e32 v6, 2, v191
	v_mov_b32_e32 v7, v159
	v_lshl_add_u64 v[116:117], v[4:5], 0, v[6:7]
	s_mov_b32 s5, 0x10000
	v_add_co_u32_e32 v44, vcc, s5, v116
	s_mov_b32 s5, 0x20000
	s_nop 0
	v_addc_co_u32_e32 v45, vcc, 0, v117, vcc
	s_mov_b64 s[12:13], 0x30000
	v_add_co_u32_e32 v52, vcc, s5, v116
	v_lshl_add_u64 v[36:37], v[116:117], 0, s[12:13]
	s_mov_b64 s[12:13], 0x10080
	v_addc_co_u32_e32 v53, vcc, 0, v117, vcc
	s_mov_b32 s5, 0x30000
	v_lshl_add_u64 v[70:71], v[116:117], 0, s[12:13]
	s_mov_b64 s[12:13], 0x20080
	s_mov_b64 s[10:11], 0x10000
	s_mov_b64 s[8:9], 0x20000
	v_add_co_u32_e32 v68, vcc, s5, v116
	v_lshl_add_u64 v[72:73], v[116:117], 0, s[12:13]
	s_mov_b64 s[12:13], 0x30080
	v_lshl_add_u64 v[20:21], v[116:117], 0, s[10:11]
	v_lshl_add_u64 v[46:47], v[116:117], 0, s[8:9]
	v_addc_co_u32_e32 v69, vcc, 0, v117, vcc
	v_lshl_add_u64 v[74:75], v[116:117], 0, s[12:13]
	s_mov_b64 s[12:13], 0x80000
	s_mov_b32 s5, 0x80000
	global_load_dwordx4 v[4:7], v[116:117], off offset:16 nt
	global_load_dwordx4 v[8:11], v[116:117], off nt
	global_load_dwordx4 v[12:15], v[44:45], off nt
	global_load_dwordx4 v[16:19], v[20:21], off offset:16 nt
	s_nop 0
	global_load_dwordx4 v[20:23], v[68:69], off nt
	global_load_dwordx4 v[24:27], v[36:37], off offset:16 nt
	global_load_dwordx4 v[28:31], v[116:117], off offset:144 nt
	global_load_dwordx4 v[32:35], v[116:117], off offset:128 nt
	s_nop 0
	global_load_dwordx4 v[36:39], v[46:47], off offset:16 nt
	global_load_dwordx4 v[40:43], v[44:45], off offset:128 nt
	s_nop 0
	global_load_dwordx4 v[44:47], v[52:53], off nt
	global_load_dwordx4 v[48:51], v[52:53], off offset:128 nt
	s_nop 0
	global_load_dwordx4 v[52:55], v[70:71], off offset:16 nt
	global_load_dwordx4 v[56:59], v[68:69], off offset:128 nt
	global_load_dwordx4 v[60:63], v[72:73], off offset:16 nt
	global_load_dwordx4 v[64:67], v[74:75], off offset:16 nt
	v_lshl_add_u64 v[72:73], v[116:117], 0, s[12:13]
	v_add_co_u32_e32 v88, vcc, s5, v116
	s_mov_b64 s[12:13], 0x90000
	s_nop 0
	v_addc_co_u32_e32 v89, vcc, 0, v117, vcc
	v_lshl_add_u64 v[84:85], v[116:117], 0, s[12:13]
	s_mov_b32 s5, 0x90000
	s_mov_b64 s[12:13], 0xa0000
	v_add_co_u32_e32 v96, vcc, s5, v116
	v_lshl_add_u64 v[80:81], v[116:117], 0, s[12:13]
	s_mov_b64 s[12:13], 0xb0000
	v_addc_co_u32_e32 v97, vcc, 0, v117, vcc
	s_mov_b32 s5, 0xa0000
	v_lshl_add_u64 v[108:109], v[116:117], 0, s[12:13]
	s_mov_b64 s[12:13], 0x80080
	v_add_co_u32_e32 v112, vcc, s5, v116
	v_lshl_add_u64 v[100:101], v[116:117], 0, s[12:13]
	s_mov_b64 s[12:13], 0x90080
	v_addc_co_u32_e32 v113, vcc, 0, v117, vcc
	s_mov_b32 s5, 0xb0000
	v_lshl_add_u64 v[104:105], v[116:117], 0, s[12:13]
	s_mov_b64 s[12:13], 0xa0080
	v_add_co_u32_e32 v120, vcc, s5, v116
	v_lshl_add_u64 v[124:125], v[116:117], 0, s[12:13]
	s_mov_b64 s[12:13], 0xb0080
	v_addc_co_u32_e32 v121, vcc, 0, v117, vcc
	v_lshl_add_u64 v[128:129], v[116:117], 0, s[12:13]
	global_load_dwordx4 v[68:71], v[88:89], off nt
	s_nop 0
	global_load_dwordx4 v[72:75], v[72:73], off offset:16 nt
	s_nop 0
	global_load_dwordx4 v[76:79], v[112:113], off nt
	s_nop 0
	global_load_dwordx4 v[80:83], v[80:81], off offset:16 nt
	s_nop 0
	global_load_dwordx4 v[84:87], v[84:85], off offset:16 nt
	s_nop 0
	global_load_dwordx4 v[88:91], v[88:89], off offset:128 nt
	s_nop 0
	global_load_dwordx4 v[92:95], v[96:97], off nt
	s_nop 0
	global_load_dwordx4 v[96:99], v[96:97], off offset:128 nt
	s_nop 0
	global_load_dwordx4 v[100:103], v[100:101], off offset:16 nt
	s_nop 0
	global_load_dwordx4 v[104:107], v[104:105], off offset:16 nt
	s_nop 0
	global_load_dwordx4 v[108:111], v[108:109], off offset:16 nt
	s_nop 0
	global_load_dwordx4 v[112:115], v[112:113], off offset:128 nt
	s_nop 0
	global_load_dwordx4 v[116:119], v[120:121], off nt
	s_nop 0
	global_load_dwordx4 v[120:123], v[120:121], off offset:128 nt
	s_nop 0
	global_load_dwordx4 v[124:127], v[124:125], off offset:16 nt
	s_nop 0
	global_load_dwordx4 v[128:131], v[128:129], off offset:16 nt

.LBB0_962:
	s_or_b64 exec, exec, s[12:13]
	s_cmp_lg_u32 s39, 0
	s_cbranch_scc1 .Lp4x_done_w0
	s_lshr_b32 s44, s39, 8
	s_lshl_b32 s52, s44, 6
	s_lshl_b32 s5, s4, 8
	s_add_i32 s5, s5, s52
	v_or_b32_e32 v4, s5, v3
	v_ashrrev_i32_e32 v5, 31, v4
	v_lshlrev_b64 v[4:5], 12, v[4:5]
	s_lshl_b32 s8, s16, 8
	s_bfe_u32 s3, s39, 0x20006
	v_lshl_add_u64 v[4:5], s[98:99], 0, v[4:5]
	s_ashr_i32 s9, s8, 31
	v_lshl_add_u64 v[4:5], s[8:9], 2, v[4:5]
	s_lshl_b32 s8, s3, 8
	s_mov_b32 s9, 0
	v_mov_b32_e32 v159, 0
	v_lshl_add_u64 v[4:5], v[4:5], 0, s[8:9]
	v_lshlrev_b32_e32 v6, 2, v191
	v_mov_b32_e32 v7, v159
	v_lshl_add_u64 v[116:117], v[4:5], 0, v[6:7]
	s_mov_b32 s5, 0x10000
	v_add_co_u32_e32 v44, vcc, s5, v116
	s_mov_b32 s5, 0x20000
	s_nop 0
	v_addc_co_u32_e32 v45, vcc, 0, v117, vcc
	s_mov_b64 s[12:13], 0x30000
	v_add_co_u32_e32 v52, vcc, s5, v116
	v_lshl_add_u64 v[36:37], v[116:117], 0, s[12:13]
	s_mov_b64 s[12:13], 0x10080
	v_addc_co_u32_e32 v53, vcc, 0, v117, vcc
	s_mov_b32 s5, 0x30000
	v_lshl_add_u64 v[70:71], v[116:117], 0, s[12:13]
	s_mov_b64 s[12:13], 0x20080
	s_mov_b64 s[10:11], 0x10000
	s_mov_b64 s[8:9], 0x20000
	v_add_co_u32_e32 v68, vcc, s5, v116
	v_lshl_add_u64 v[72:73], v[116:117], 0, s[12:13]
	s_mov_b64 s[12:13], 0x30080
	v_lshl_add_u64 v[20:21], v[116:117], 0, s[10:11]
	v_lshl_add_u64 v[46:47], v[116:117], 0, s[8:9]
	v_addc_co_u32_e32 v69, vcc, 0, v117, vcc
	v_lshl_add_u64 v[74:75], v[116:117], 0, s[12:13]
	s_mov_b64 s[12:13], 0x80000
	s_mov_b32 s5, 0x80000
	global_load_dwordx4 v[4:7], v[116:117], off offset:16 nt
	global_load_dwordx4 v[8:11], v[116:117], off nt
	global_load_dwordx4 v[12:15], v[44:45], off nt
	global_load_dwordx4 v[16:19], v[20:21], off offset:16 nt
	s_nop 0
	global_load_dwordx4 v[20:23], v[68:69], off nt
	global_load_dwordx4 v[24:27], v[36:37], off offset:16 nt
	global_load_dwordx4 v[28:31], v[116:117], off offset:144 nt
	global_load_dwordx4 v[32:35], v[116:117], off offset:128 nt
	s_nop 0
	global_load_dwordx4 v[36:39], v[46:47], off offset:16 nt
	global_load_dwordx4 v[40:43], v[44:45], off offset:128 nt
	s_nop 0
	global_load_dwordx4 v[44:47], v[52:53], off nt
	global_load_dwordx4 v[48:51], v[52:53], off offset:128 nt
	s_nop 0
	global_load_dwordx4 v[52:55], v[70:71], off offset:16 nt
	global_load_dwordx4 v[56:59], v[68:69], off offset:128 nt
	global_load_dwordx4 v[60:63], v[72:73], off offset:16 nt
	global_load_dwordx4 v[64:67], v[74:75], off offset:16 nt
	v_lshl_add_u64 v[72:73], v[116:117], 0, s[12:13]
	v_add_co_u32_e32 v88, vcc, s5, v116
	s_mov_b64 s[12:13], 0x90000
	s_nop 0
	v_addc_co_u32_e32 v89, vcc, 0, v117, vcc
	v_lshl_add_u64 v[84:85], v[116:117], 0, s[12:13]
	s_mov_b32 s5, 0x90000
	s_mov_b64 s[12:13], 0xa0000
	v_add_co_u32_e32 v96, vcc, s5, v116
	v_lshl_add_u64 v[80:81], v[116:117], 0, s[12:13]
	s_mov_b64 s[12:13], 0xb0000
	v_addc_co_u32_e32 v97, vcc, 0, v117, vcc
	s_mov_b32 s5, 0xa0000
	v_lshl_add_u64 v[108:109], v[116:117], 0, s[12:13]
	s_mov_b64 s[12:13], 0x80080
	v_add_co_u32_e32 v112, vcc, s5, v116
	v_lshl_add_u64 v[100:101], v[116:117], 0, s[12:13]
	s_mov_b64 s[12:13], 0x90080
	v_addc_co_u32_e32 v113, vcc, 0, v117, vcc
	s_mov_b32 s5, 0xb0000
	v_lshl_add_u64 v[104:105], v[116:117], 0, s[12:13]
	s_mov_b64 s[12:13], 0xa0080
	v_add_co_u32_e32 v120, vcc, s5, v116
	v_lshl_add_u64 v[124:125], v[116:117], 0, s[12:13]
	s_mov_b64 s[12:13], 0xb0080
	v_addc_co_u32_e32 v121, vcc, 0, v117, vcc
	v_lshl_add_u64 v[128:129], v[116:117], 0, s[12:13]
	global_load_dwordx4 v[68:71], v[88:89], off nt
	s_nop 0
	global_load_dwordx4 v[72:75], v[72:73], off offset:16 nt
	s_nop 0
	global_load_dwordx4 v[76:79], v[112:113], off nt
	s_nop 0
	global_load_dwordx4 v[80:83], v[80:81], off offset:16 nt
	s_nop 0
	global_load_dwordx4 v[84:87], v[84:85], off offset:16 nt
	s_nop 0
	global_load_dwordx4 v[88:91], v[88:89], off offset:128 nt
	s_nop 0
	global_load_dwordx4 v[92:95], v[96:97], off nt
	s_nop 0
	global_load_dwordx4 v[96:99], v[96:97], off offset:128 nt
	s_nop 0
	global_load_dwordx4 v[100:103], v[100:101], off offset:16 nt
	s_nop 0
	global_load_dwordx4 v[104:107], v[104:105], off offset:16 nt
	s_nop 0
	global_load_dwordx4 v[108:111], v[108:109], off offset:16 nt
	s_nop 0
	global_load_dwordx4 v[112:115], v[112:113], off offset:128 nt
	s_nop 0
	global_load_dwordx4 v[116:119], v[120:121], off nt
	s_nop 0
	global_load_dwordx4 v[120:123], v[120:121], off offset:128 nt
	s_nop 0
	global_load_dwordx4 v[124:127], v[124:125], off offset:16 nt
	s_nop 0
	global_load_dwordx4 v[128:131], v[128:129], off offset:16 nt
	s_lshr_b32 s5, s39, 6
